# stack on the LN-DPP version: LN4 and gla_out DPP sums, DSA unit prologue reorder, P0 x-convert 4x unroll
# speedup vs baseline: 1.0058x; 1.0011x over previous
; __device__ __forceinline__ void gla_out_phase(int wv, const Args& A, int G) {
;     ...
;         for (int u = 0; u < 2; ++u) { const int row = row0 + u; const size_t tok = (size_t)(row >> 2); const int h = row & 3;
;             o4[u] = __builtin_bit_cast(h16x4, *(const u32x2*)(MIX + tok * DM + 1024 + h * 256 + lane * 4));
;             gr[u] = __builtin_bit_cast(h16x4, *(const u32x2*)(PROJ + tok * PW + C_GR + h * 256 + lane * 4));
;             gn[u] = *(const f32x4*)(A.in[18] + h * 256 + lane * 4); }
; #pragma unroll
;         for (int u = 0; u < 2; ++u) { const int row = row0 + u; const size_t tok = (size_t)(row >> 2); const int h = row & 3;
;             float x[4]; float s = 0.f;
; #pragma unroll
;             for (int r = 0; r < 4; ++r) { x[r] = (float)o4[u][r]; s += x[r]; }
;             const float mean = wave_sum(s) * (1.f / 256.f); float q = 0.f;
; #pragma unroll
;             for (int r = 0; r < 4; ++r) { x[r] -= mean; q += x[r] * x[r]; }
;             const float rstd = 1.f / sqrtf(wave_sum(q) * (1.f / 256.f) + LN_EPS); h16x4 y;
.LBB0_2122:
	v_ashrrev_i32_e32 v6, 2, v8
	v_ashrrev_i32_e32 v7, 31, v6
	v_lshlrev_b64 v[12:13], 12, v[6:7]
	v_and_b32_e32 v16, 0x200, v9
	v_lshl_add_u64 v[12:13], s[44:45], 0, v[12:13]
	v_add_u32_e32 v8, s0, v8
	v_lshlrev_b32_e32 v0, 1, v16
	v_lshl_add_u64 v[14:15], v[12:13], 0, v[4:5]
	v_cmp_lt_i32_e32 vcc, s19, v8
	v_mad_i64_i32 v[6:7], s[6:7], v6, s3, v[12:13]
	v_lshl_add_u64 v[12:13], v[14:15], 0, v[0:1]
	s_or_b64 s[12:13], vcc, s[12:13]
	v_add_co_u32_e32 v22, vcc, s4, v12
	v_lshl_add_u64 v[6:7], v[6:7], 0, v[4:5]
	s_nop 0
	v_addc_co_u32_e32 v23, vcc, 0, v13, vcc
	v_lshl_add_u64 v[6:7], v[6:7], 0, v[0:1]
	v_lshlrev_b32_e32 v0, 2, v16
	global_load_dwordx2 v[28:29], v[22:23], off offset:2048
	v_lshl_add_u64 v[24:25], v[6:7], 0, s[16:17]
	v_add_co_u32_e32 v6, vcc, s5, v6
	v_lshl_add_u64 v[26:27], v[2:3], 0, v[0:1]
	v_lshl_add_u64 v[20:21], v[12:13], 0, s[14:15]
	v_addc_co_u32_e32 v7, vcc, 0, v7, vcc
	global_load_dwordx4 v[12:15], v[26:27], off
	global_load_dwordx4 v[16:19], v[26:27], off offset:1024
	global_load_dwordx2 v[30:31], v[6:7], off offset:1536
	global_load_dwordx2 v[32:33], v[24:25], off offset:512
	global_load_dwordx2 v[34:35], v[20:21], off offset:512
	v_add_u32_e32 v9, s1, v9
	s_waitcnt vmcnt(5)
	v_cvt_f32_f16_e32 v6, v28
	v_cvt_f32_f16_sdwa v7, v28 dst_sel:DWORD dst_unused:UNUSED_PAD src0_sel:WORD_1
	v_cvt_f32_f16_e32 v24, v29
	v_cvt_f32_f16_sdwa v25, v29 dst_sel:DWORD dst_unused:UNUSED_PAD src0_sel:WORD_1
	v_add_f32_e32 v0, 0, v6
	v_add_f32_e32 v0, v0, v7
	s_waitcnt vmcnt(2)
	v_cvt_f32_f16_e32 v26, v30
	v_cvt_f32_f16_sdwa v27, v30 dst_sel:DWORD dst_unused:UNUSED_PAD src0_sel:WORD_1
	s_waitcnt vmcnt(0)
	v_cvt_f32_f16_e32 v30, v34
	v_cvt_f32_f16_e32 v28, v31
	v_cvt_f32_f16_sdwa v29, v31 dst_sel:DWORD dst_unused:UNUSED_PAD src0_sel:WORD_1
	v_cvt_f32_f16_sdwa v31, v34 dst_sel:DWORD dst_unused:UNUSED_PAD src0_sel:WORD_1
	v_cvt_f32_f16_e32 v34, v35
	v_cvt_f32_f16_e32 v36, v32
	v_cvt_f32_f16_sdwa v37, v32 dst_sel:DWORD dst_unused:UNUSED_PAD src0_sel:WORD_1
	v_cvt_f32_f16_sdwa v35, v35 dst_sel:DWORD dst_unused:UNUSED_PAD src0_sel:WORD_1
	v_cvt_f32_f16_e32 v32, v33
	v_cvt_f32_f16_sdwa v33, v33 dst_sel:DWORD dst_unused:UNUSED_PAD src0_sel:WORD_1
	v_mul_f32_e32 v38, 0xbfb8aa3b, v26
	v_mul_f32_e32 v39, 0xbfb8aa3b, v27
	v_add_f32_e32 v42, 0, v30
	v_add_f32_e32 v0, v0, v24
	v_exp_f32_e32 v38, v38
	v_exp_f32_e32 v39, v39
	v_add_f32_e32 v42, v42, v31
	v_add_f32_e32 v0, v0, v25
	v_add_f32_e32 v42, v42, v34
	v_mov_b32_e32 v177, v0
	v_mul_f32_e32 v43, 0xbfb8aa3b, v36
	v_mul_f32_e32 v44, 0xbfb8aa3b, v37
	v_mul_f32_e32 v45, 0xbfb8aa3b, v32
	v_mul_f32_e32 v46, 0xbfb8aa3b, v33
	v_add_f32_e32 v48, v42, v35
	v_exp_f32_e32 v43, v43
	v_exp_f32_e32 v44, v44
	v_exp_f32_e32 v45, v45
	v_exp_f32_e32 v46, v46
	v_mov_b32_e32 v178, v48
	v_add_f32_e32 v38, 1.0, v38
	v_add_f32_e32 v39, 1.0, v39
	v_mul_f32_e32 v40, 0xbfb8aa3b, v28
	v_mul_f32_e32 v41, 0xbfb8aa3b, v29
	v_rcp_f32_e32 v38, v38
	v_rcp_f32_e32 v39, v39
	v_exp_f32_e32 v40, v40
	v_exp_f32_e32 v41, v41
	v_add_f32_e32 v42, 1.0, v43
	v_add_f32_e32 v43, 1.0, v44
	v_add_f32_e32 v44, 1.0, v45
	v_add_f32_e32 v45, 1.0, v46
	v_pk_mul_f32 v[26:27], v[38:39], v[26:27]
	v_add_f32_e32 v40, 1.0, v40
	v_add_f32_e32 v41, 1.0, v41
	v_rcp_f32_e32 v40, v40
	v_rcp_f32_e32 v41, v41
	s_nop 0
	v_pk_mul_f32 v[28:29], v[40:41], v[28:29]
	v_rcp_f32_e32 v42, v42
	v_rcp_f32_e32 v43, v43
	v_rcp_f32_e32 v44, v44
	s_nop 0
	v_pk_mul_f32 v[36:37], v[42:43], v[36:37]
	v_rcp_f32_e32 v45, v45
	s_nop 0
	v_pk_mul_f32 v[32:33], v[44:45], v[32:33]
	s_nop 1
	v_add_f32_dpp v177, v177, v177 row_shr:1 row_mask:0xf bank_mask:0xf
	s_nop 1
	v_add_f32_dpp v177, v177, v177 row_shr:2 row_mask:0xf bank_mask:0xf
	s_nop 1
	v_add_f32_dpp v177, v177, v177 row_shr:4 row_mask:0xf bank_mask:0xf
	s_nop 1
	v_add_f32_dpp v177, v177, v177 row_shr:8 row_mask:0xf bank_mask:0xf
	s_nop 1
	v_add_f32_dpp v177, v177, v177 row_bcast:15 row_mask:0xa bank_mask:0xf
	s_nop 1
	v_add_f32_dpp v177, v177, v177 row_bcast:31 row_mask:0xc bank_mask:0xf
	s_nop 0
	v_readlane_b32 s32, v177, 63
	s_nop 1
	v_mov_b32_e32 v0, s32
	v_mul_f32_e32 v0, 0x3b800000, v0
	v_pk_add_f32 v[6:7], v[6:7], v[0:1] op_sel_hi:[1,0] neg_lo:[0,1] neg_hi:[0,1]
	s_nop 1
	v_add_f32_dpp v178, v178, v178 row_shr:1 row_mask:0xf bank_mask:0xf
	s_nop 1
	v_add_f32_dpp v178, v178, v178 row_shr:2 row_mask:0xf bank_mask:0xf
	s_nop 1
	v_add_f32_dpp v178, v178, v178 row_shr:4 row_mask:0xf bank_mask:0xf
	s_nop 1
	v_add_f32_dpp v178, v178, v178 row_shr:8 row_mask:0xf bank_mask:0xf
	s_nop 1
	v_add_f32_dpp v178, v178, v178 row_bcast:15 row_mask:0xa bank_mask:0xf
	s_nop 1
	v_add_f32_dpp v178, v178, v178 row_bcast:31 row_mask:0xc bank_mask:0xf
; __device__ __forceinline__ void gla_out_phase(int wv, const Args& A, int G) {
;     ...
;             const float mean = wave_sum(s) * (1.f / 256.f); float q = 0.f;
; #pragma unroll
;             for (int r = 0; r < 4; ++r) { x[r] -= mean; q += x[r] * x[r]; }
;             const float rstd = 1.f / sqrtf(wave_sum(q) * (1.f / 256.f) + LN_EPS); h16x4 y;
; #pragma unroll
;             for (int r = 0; r < 4; ++r) { const float g = (float)gr[u][r]; y[r] = (h16)(x[r] * rstd * gn[u][r] * (g * __builtin_amdgcn_rcpf(1.f + __expf(-g)))); }
;             *(u32x2*)(MIX + tok * DM + 1024 + h * 256 + lane * 4) = __builtin_bit_cast(u32x2, y); }
	s_nop 0
	v_readlane_b32 s32, v178, 63
	s_nop 1
	v_mov_b32_e32 v38, s32
	v_pk_add_f32 v[24:25], v[24:25], v[0:1] op_sel_hi:[1,0] neg_lo:[0,1] neg_hi:[0,1]
	v_mul_f32_e32 v0, 0x3b800000, v38
	v_pk_mul_f32 v[38:39], v[6:7], v[6:7]
	v_pk_mul_f32 v[40:41], v[24:25], v[24:25]
	v_pk_add_f32 v[30:31], v[30:31], v[0:1] op_sel_hi:[1,0] neg_lo:[0,1] neg_hi:[0,1]
	v_pk_add_f32 v[34:35], v[34:35], v[0:1] op_sel_hi:[1,0] neg_lo:[0,1] neg_hi:[0,1]
	v_add_f32_e32 v0, v38, v39
	v_pk_mul_f32 v[38:39], v[30:31], v[30:31]
	v_add_f32_e32 v0, v40, v0
	v_pk_mul_f32 v[42:43], v[34:35], v[34:35]
	v_add_f32_e32 v38, v38, v39
	v_add_f32_e32 v0, v41, v0
	v_add_f32_e32 v38, v42, v38
	v_mov_b32_e32 v179, v0
	v_add_f32_e32 v38, v43, v38
	v_mov_b32_e32 v180, v38
	s_nop 1
	v_add_f32_dpp v179, v179, v179 row_shr:1 row_mask:0xf bank_mask:0xf
	s_nop 1
	v_add_f32_dpp v179, v179, v179 row_shr:2 row_mask:0xf bank_mask:0xf
	s_nop 1
	v_add_f32_dpp v179, v179, v179 row_shr:4 row_mask:0xf bank_mask:0xf
	s_nop 1
	v_add_f32_dpp v179, v179, v179 row_shr:8 row_mask:0xf bank_mask:0xf
	s_nop 1
	v_add_f32_dpp v179, v179, v179 row_bcast:15 row_mask:0xa bank_mask:0xf
	s_nop 1
	v_add_f32_dpp v179, v179, v179 row_bcast:31 row_mask:0xc bank_mask:0xf
	s_nop 0
	v_readlane_b32 s32, v179, 63
	s_nop 1
	v_mov_b32_e32 v0, s32
	v_fmamk_f32 v0, v0, 0x3b800000, v10
	s_nop 1
	v_add_f32_dpp v180, v180, v180 row_shr:1 row_mask:0xf bank_mask:0xf
	s_nop 1
	v_add_f32_dpp v180, v180, v180 row_shr:2 row_mask:0xf bank_mask:0xf
	s_nop 1
	v_add_f32_dpp v180, v180, v180 row_shr:4 row_mask:0xf bank_mask:0xf
	s_nop 1
	v_add_f32_dpp v180, v180, v180 row_shr:8 row_mask:0xf bank_mask:0xf
	s_nop 1
	v_add_f32_dpp v180, v180, v180 row_bcast:15 row_mask:0xa bank_mask:0xf
	s_nop 1
	v_add_f32_dpp v180, v180, v180 row_bcast:31 row_mask:0xc bank_mask:0xf
	s_nop 0
	v_readlane_b32 s32, v180, 63
	s_nop 1
	v_mov_b32_e32 v38, s32
	v_mul_f32_e32 v39, 0x4f800000, v0
	v_cmp_gt_f32_e32 vcc, s18, v0
	v_fmamk_f32 v38, v38, 0x3b800000, v10
	v_cmp_gt_f32_e64 s[6:7], s18, v38
	v_cndmask_b32_e32 v0, v0, v39, vcc
	v_mul_f32_e32 v39, 0x4f800000, v38
	v_sqrt_f32_e32 v40, v0
	v_cndmask_b32_e64 v38, v38, v39, s[6:7]
	v_sqrt_f32_e32 v39, v38
	v_add_u32_e32 v41, -1, v40
	v_add_u32_e32 v42, 1, v40
	v_fma_f32 v43, -v41, v40, v0
	v_fma_f32 v44, -v42, v40, v0
	v_add_u32_e32 v45, -1, v39
	v_cmp_ge_f32_e64 s[8:9], 0, v43
	v_add_u32_e32 v46, 1, v39
	v_fma_f32 v43, -v46, v39, v38
	v_cndmask_b32_e64 v40, v40, v41, s[8:9]
	v_fma_f32 v41, -v45, v39, v38
	v_cmp_lt_f32_e64 s[8:9], 0, v44
	s_nop 1
	v_cndmask_b32_e64 v40, v40, v42, s[8:9]
	v_cmp_ge_f32_e64 s[8:9], 0, v41
	v_mul_f32_e32 v41, 0x37800000, v40
	v_cndmask_b32_e32 v40, v40, v41, vcc
	v_cndmask_b32_e64 v39, v39, v45, s[8:9]
	v_cmp_lt_f32_e64 s[8:9], 0, v43
	v_cmp_class_f32_e32 vcc, v0, v11
	s_nop 0
	v_cndmask_b32_e64 v39, v39, v46, s[8:9]
	v_mul_f32_e32 v41, 0x37800000, v39
	v_cndmask_b32_e32 v0, v40, v0, vcc
	v_cndmask_b32_e64 v39, v39, v41, s[6:7]
	v_cmp_class_f32_e32 vcc, v38, v11
	v_div_scale_f32 v40, s[6:7], v0, v0, 1.0
	s_nop 0
	v_cndmask_b32_e32 v38, v39, v38, vcc
	v_rcp_f32_e32 v39, v40
	v_div_scale_f32 v42, s[8:9], v38, v38, 1.0
	v_rcp_f32_e32 v44, v42
	v_fma_f32 v45, -v40, v39, 1.0
	v_div_scale_f32 v41, s[6:7], 1.0, v0, 1.0
	v_fmac_f32_e32 v39, v45, v39
	v_fma_f32 v45, -v42, v44, 1.0
	v_div_scale_f32 v43, s[8:9], 1.0, v38, 1.0
	v_mul_f32_e32 v46, v41, v39
	v_fmac_f32_e32 v44, v45, v44
	v_fma_f32 v45, -v40, v46, v41
	v_mul_f32_e32 v47, v43, v44
	v_fmac_f32_e32 v46, v45, v39
	v_fma_f32 v45, -v42, v47, v43
	v_fma_f32 v40, -v40, v46, v41
	v_fmac_f32_e32 v47, v45, v44
	s_mov_b64 vcc, s[6:7]
	v_div_fmas_f32 v39, v40, v39, v46
	v_fma_f32 v40, -v42, v47, v43
	s_mov_b64 vcc, s[8:9]
	v_div_fixup_f32 v0, v39, v0, 1.0
	v_div_fmas_f32 v39, v40, v44, v47
	v_pk_mul_f32 v[6:7], v[6:7], v[0:1] op_sel_hi:[1,0]
	v_pk_mul_f32 v[24:25], v[24:25], v[0:1] op_sel_hi:[1,0]
	v_div_fixup_f32 v0, v39, v38, 1.0
	v_pk_mul_f32 v[6:7], v[12:13], v[6:7]
	v_pk_mul_f32 v[12:13], v[14:15], v[24:25]
	v_pk_mul_f32 v[14:15], v[30:31], v[0:1] op_sel_hi:[1,0]
	v_pk_mul_f32 v[24:25], v[34:35], v[0:1] op_sel_hi:[1,0]
	v_pk_mul_f32 v[6:7], v[26:27], v[6:7]
	v_pk_mul_f32 v[12:13], v[28:29], v[12:13]
	v_pk_mul_f32 v[14:15], v[16:17], v[14:15]
	v_pk_mul_f32 v[16:17], v[18:19], v[24:25]
	v_cvt_pk_f16_f32 v6, v6, v7
	v_cvt_pk_f16_f32 v7, v12, v13
	v_pk_mul_f32 v[12:13], v[36:37], v[14:15]
	v_pk_mul_f32 v[14:15], v[32:33], v[16:17]
	global_store_dwordx2 v[22:23], v[6:7], off offset:2048
	v_cvt_pk_f16_f32 v6, v12, v13
	v_cvt_pk_f16_f32 v7, v14, v15
	global_store_dwordx2 v[20:21], v[6:7], off offset:512
	s_andn2_b64 exec, exec, s[12:13]
	s_cbranch_execnz .LBB0_2122
